# gate/up GEMM: the two wave halves no longer align their epilogues (two conditional barriers per tile removed, offset undone once before the last epilogue): one half's SwiGLU epilogue overlaps the othe
# baseline (speedup 1.0000x reference)
.LBB0_50:
	s_add_u32 s8, s58, 0xfffc0080
	s_addc_u32 s9, s59, -1
	s_add_i32 s10, 0, 0x10000
	s_cmp_eq_u32 s85, 12
	s_cselect_b32 s41, s53, s9
	s_cselect_b32 s40, s69, s8
	s_cselect_b32 s29, s51, s84
	s_cselect_b32 s28, s72, s73
	s_add_i32 s11, 0, 0x14000
	v_add_u32_e32 v158, s10, v150
	v_add_u32_e32 v174, s11, v150
	ds_read_b128 v[142:145], v158
	ds_read_b128 v[146:149], v158 offset:1024
	ds_read_b128 v[154:157], v158 offset:2048
	ds_read_b128 v[158:161], v158 offset:3072
	ds_read_b128 v[162:165], v174
	ds_read_b128 v[166:169], v174 offset:1024
	ds_read_b128 v[170:173], v174 offset:2048
	ds_read_b128 v[174:177], v174 offset:3072
	v_lshl_add_u64 v[210:211], s[58:59], 0, v[138:139]
	s_add_i32 m0, s61, 0xc000
	ds_read_b128 v[178:181], v153
	ds_read_b128 v[182:185], v153 offset:1024
	ds_read_b128 v[186:189], v153 offset:2048
	ds_read_b128 v[190:193], v153 offset:3072
	ds_read_b128 v[194:197], v153 offset:4096
	ds_read_b128 v[198:201], v153 offset:5120
	ds_read_b128 v[202:205], v153 offset:6144
	ds_read_b128 v[206:209], v153 offset:7168
	global_load_lds_dwordx4 v[210:211], off
	v_lshl_add_u64 v[210:211], s[58:59], 0, v[140:141]
	s_add_i32 m0, s61, 0xe000
	s_nop 0
	global_load_lds_dwordx4 v[210:211], off
	s_waitcnt vmcnt(8)
	s_waitcnt lgkmcnt(0)
	s_setprio 1
	s_barrier
	v_mfma_f32_16x16x32_bf16 v[126:129], v[142:145], v[178:181], v[126:129]
	v_mfma_f32_16x16x32_bf16 v[118:121], v[154:157], v[178:181], v[118:121]
	v_mfma_f32_16x16x32_bf16 v[110:113], v[142:145], v[186:189], v[110:113]
	v_mfma_f32_16x16x32_bf16 v[102:105], v[154:157], v[186:189], v[102:105]
	v_mfma_f32_16x16x32_bf16 v[94:97], v[142:145], v[194:197], v[94:97]
	v_mfma_f32_16x16x32_bf16 v[86:89], v[154:157], v[194:197], v[86:89]
	v_mfma_f32_16x16x32_bf16 v[78:81], v[142:145], v[202:205], v[78:81]
	v_mfma_f32_16x16x32_bf16 v[70:73], v[154:157], v[202:205], v[70:73]
	v_mfma_f32_16x16x32_bf16 v[126:129], v[146:149], v[182:185], v[126:129]
	v_mfma_f32_16x16x32_bf16 v[118:121], v[158:161], v[182:185], v[118:121]
	v_mfma_f32_16x16x32_bf16 v[110:113], v[146:149], v[190:193], v[110:113]
	v_mfma_f32_16x16x32_bf16 v[102:105], v[158:161], v[190:193], v[102:105]
	v_mfma_f32_16x16x32_bf16 v[94:97], v[146:149], v[198:201], v[94:97]
	v_mfma_f32_16x16x32_bf16 v[86:89], v[158:161], v[198:201], v[86:89]
	v_mfma_f32_16x16x32_bf16 v[78:81], v[146:149], v[206:209], v[78:81]
	v_mfma_f32_16x16x32_bf16 v[70:73], v[158:161], v[206:209], v[70:73]
	v_mfma_f32_16x16x32_bf16 v[122:125], v[162:165], v[178:181], v[122:125]
	v_mfma_f32_16x16x32_bf16 v[114:117], v[170:173], v[178:181], v[114:117]
	v_mfma_f32_16x16x32_bf16 v[106:109], v[162:165], v[186:189], v[106:109]
	v_mfma_f32_16x16x32_bf16 v[98:101], v[170:173], v[186:189], v[98:101]
	v_mfma_f32_16x16x32_bf16 v[90:93], v[162:165], v[194:197], v[90:93]
	v_mfma_f32_16x16x32_bf16 v[82:85], v[170:173], v[194:197], v[82:85]
	v_mfma_f32_16x16x32_bf16 v[74:77], v[162:165], v[202:205], v[74:77]
	v_mfma_f32_16x16x32_bf16 v[66:69], v[170:173], v[202:205], v[66:69]
	v_mfma_f32_16x16x32_bf16 v[122:125], v[166:169], v[182:185], v[122:125]
	v_mfma_f32_16x16x32_bf16 v[114:117], v[174:177], v[182:185], v[114:117]
	v_mfma_f32_16x16x32_bf16 v[106:109], v[166:169], v[190:193], v[106:109]
	v_mfma_f32_16x16x32_bf16 v[98:101], v[174:177], v[190:193], v[98:101]
	v_mfma_f32_16x16x32_bf16 v[90:93], v[166:169], v[198:201], v[90:93]
	v_mfma_f32_16x16x32_bf16 v[82:85], v[174:177], v[198:201], v[82:85]
	v_mfma_f32_16x16x32_bf16 v[74:77], v[166:169], v[206:209], v[74:77]
	v_mfma_f32_16x16x32_bf16 v[66:69], v[174:177], v[206:209], v[66:69]
	s_barrier
	s_setprio 0
	s_add_i32 s8, s10, s31
	v_lshl_add_u64 v[210:211], s[28:29], 0, v[130:131]
	s_mov_b32 m0, s8
	ds_read_b128 v[178:181], v153 offset:16384
	ds_read_b128 v[182:185], v153 offset:17408
	ds_read_b128 v[186:189], v153 offset:18432
	ds_read_b128 v[190:193], v153 offset:19456
	ds_read_b128 v[194:197], v153 offset:20480
	ds_read_b128 v[198:201], v153 offset:21504
	ds_read_b128 v[202:205], v153 offset:22528
	ds_read_b128 v[206:209], v153 offset:23552
	global_load_lds_dwordx4 v[210:211], off
	s_add_i32 m0, s8, 0x2000
	s_add_u32 s8, s28, 0x40000
	v_lshl_add_u64 v[212:213], s[28:29], 0, v[132:133]
	s_addc_u32 s9, s29, 0
	s_add_i32 s10, s11, s31
	global_load_lds_dwordx4 v[212:213], off
	v_lshl_add_u64 v[214:215], s[8:9], 0, v[130:131]
	s_mov_b32 m0, s10
	v_lshl_add_u64 v[216:217], s[40:41], 0, v[134:135]
	global_load_lds_dwordx4 v[214:215], off
	v_lshl_add_u64 v[214:215], s[8:9], 0, v[132:133]
	s_add_i32 m0, s10, 0x2000
	s_nop 0
	global_load_lds_dwordx4 v[214:215], off
	v_lshl_add_u64 v[214:215], s[40:41], 0, v[136:137]
	s_mov_b32 m0, s61
	s_nop 0
	global_load_lds_dwordx4 v[214:215], off
	s_mov_b32 m0, s62
	s_nop 0
	global_load_lds_dwordx4 v[216:217], off
	s_waitcnt vmcnt(8)
	s_waitcnt lgkmcnt(0)
	s_setprio 1
	s_barrier
	v_mfma_f32_16x16x32_bf16 v[62:65], v[142:145], v[178:181], v[62:65]
	v_mfma_f32_16x16x32_bf16 v[54:57], v[154:157], v[178:181], v[54:57]
	v_mfma_f32_16x16x32_bf16 v[46:49], v[142:145], v[186:189], v[46:49]
	v_mfma_f32_16x16x32_bf16 v[38:41], v[154:157], v[186:189], v[38:41]
	v_mfma_f32_16x16x32_bf16 v[30:33], v[142:145], v[194:197], v[30:33]
	v_mfma_f32_16x16x32_bf16 v[22:25], v[154:157], v[194:197], v[22:25]
	v_mfma_f32_16x16x32_bf16 v[14:17], v[142:145], v[202:205], v[14:17]
	v_mfma_f32_16x16x32_bf16 v[6:9], v[154:157], v[202:205], v[6:9]
	v_mfma_f32_16x16x32_bf16 v[62:65], v[146:149], v[182:185], v[62:65]
	v_mfma_f32_16x16x32_bf16 v[54:57], v[158:161], v[182:185], v[54:57]
	v_mfma_f32_16x16x32_bf16 v[46:49], v[146:149], v[190:193], v[46:49]
	v_mfma_f32_16x16x32_bf16 v[38:41], v[158:161], v[190:193], v[38:41]
	v_mfma_f32_16x16x32_bf16 v[30:33], v[146:149], v[198:201], v[30:33]
	v_mfma_f32_16x16x32_bf16 v[22:25], v[158:161], v[198:201], v[22:25]
	v_mfma_f32_16x16x32_bf16 v[14:17], v[146:149], v[206:209], v[14:17]
	v_mfma_f32_16x16x32_bf16 v[6:9], v[158:161], v[206:209], v[6:9]
	v_mfma_f32_16x16x32_bf16 v[58:61], v[162:165], v[178:181], v[58:61]
	v_mfma_f32_16x16x32_bf16 v[50:53], v[170:173], v[178:181], v[50:53]
	v_mfma_f32_16x16x32_bf16 v[42:45], v[162:165], v[186:189], v[42:45]
	v_mfma_f32_16x16x32_bf16 v[34:37], v[170:173], v[186:189], v[34:37]
	v_mfma_f32_16x16x32_bf16 v[26:29], v[162:165], v[194:197], v[26:29]
	v_mfma_f32_16x16x32_bf16 v[18:21], v[170:173], v[194:197], v[18:21]
	v_mfma_f32_16x16x32_bf16 v[10:13], v[162:165], v[202:205], v[10:13]
	v_mfma_f32_16x16x32_bf16 v[2:5], v[170:173], v[202:205], v[2:5]
	v_mfma_f32_16x16x32_bf16 v[58:61], v[166:169], v[182:185], v[58:61]
	v_mfma_f32_16x16x32_bf16 v[50:53], v[174:177], v[182:185], v[50:53]
	v_mfma_f32_16x16x32_bf16 v[42:45], v[166:169], v[190:193], v[42:45]
	v_mfma_f32_16x16x32_bf16 v[34:37], v[174:177], v[190:193], v[34:37]
	v_mfma_f32_16x16x32_bf16 v[26:29], v[166:169], v[198:201], v[26:29]
	v_mfma_f32_16x16x32_bf16 v[18:21], v[174:177], v[198:201], v[18:21]
	v_mfma_f32_16x16x32_bf16 v[10:13], v[166:169], v[206:209], v[10:13]
	v_mfma_f32_16x16x32_bf16 v[2:5], v[174:177], v[206:209], v[2:5]
	s_barrier
	s_setprio 0
	s_add_i32 s10, 0, 0x18000
	s_add_i32 s11, 0, 0x1c000
	v_add_u32_e32 v158, s10, v150
	v_add_u32_e32 v174, s11, v150
	ds_read_b128 v[142:145], v158
	ds_read_b128 v[146:149], v158 offset:1024
	ds_read_b128 v[154:157], v158 offset:2048
	ds_read_b128 v[158:161], v158 offset:3072
	ds_read_b128 v[162:165], v174
	ds_read_b128 v[166:169], v174 offset:1024
	ds_read_b128 v[170:173], v174 offset:2048
	ds_read_b128 v[174:177], v174 offset:3072
	s_add_u32 s8, s40, 0x40000
	s_addc_u32 s9, s41, 0
	s_mov_b32 m0, s63
	v_lshl_add_u64 v[218:219], s[8:9], 0, v[136:137]
	ds_read_b128 v[178:181], v153 offset:32768
	ds_read_b128 v[182:185], v153 offset:33792
	ds_read_b128 v[186:189], v153 offset:34816
	ds_read_b128 v[190:193], v153 offset:35840
	ds_read_b128 v[194:197], v153 offset:36864
	ds_read_b128 v[198:201], v153 offset:37888
	ds_read_b128 v[202:205], v153 offset:38912
	ds_read_b128 v[206:209], v153 offset:39936
	global_load_lds_dwordx4 v[218:219], off
	v_lshl_add_u64 v[218:219], s[8:9], 0, v[134:135]
	s_mov_b32 m0, s64
	s_nop 0
	global_load_lds_dwordx4 v[218:219], off
	s_waitcnt vmcnt(8)
	s_waitcnt lgkmcnt(0)
	s_setprio 1
	s_barrier
	v_mfma_f32_16x16x32_bf16 v[126:129], v[142:145], v[178:181], v[126:129]
	v_mfma_f32_16x16x32_bf16 v[118:121], v[154:157], v[178:181], v[118:121]
	v_mfma_f32_16x16x32_bf16 v[110:113], v[142:145], v[186:189], v[110:113]
	v_mfma_f32_16x16x32_bf16 v[102:105], v[154:157], v[186:189], v[102:105]
	v_mfma_f32_16x16x32_bf16 v[94:97], v[142:145], v[194:197], v[94:97]
	v_mfma_f32_16x16x32_bf16 v[86:89], v[154:157], v[194:197], v[86:89]
	v_mfma_f32_16x16x32_bf16 v[78:81], v[142:145], v[202:205], v[78:81]
	v_mfma_f32_16x16x32_bf16 v[70:73], v[154:157], v[202:205], v[70:73]
	v_mfma_f32_16x16x32_bf16 v[126:129], v[146:149], v[182:185], v[126:129]
	v_mfma_f32_16x16x32_bf16 v[118:121], v[158:161], v[182:185], v[118:121]
	v_mfma_f32_16x16x32_bf16 v[110:113], v[146:149], v[190:193], v[110:113]
	v_mfma_f32_16x16x32_bf16 v[102:105], v[158:161], v[190:193], v[102:105]
	v_mfma_f32_16x16x32_bf16 v[94:97], v[146:149], v[198:201], v[94:97]
	v_mfma_f32_16x16x32_bf16 v[86:89], v[158:161], v[198:201], v[86:89]
	v_mfma_f32_16x16x32_bf16 v[78:81], v[146:149], v[206:209], v[78:81]
	v_mfma_f32_16x16x32_bf16 v[70:73], v[158:161], v[206:209], v[70:73]
	v_mfma_f32_16x16x32_bf16 v[122:125], v[162:165], v[178:181], v[122:125]
	v_mfma_f32_16x16x32_bf16 v[114:117], v[170:173], v[178:181], v[114:117]
	v_mfma_f32_16x16x32_bf16 v[106:109], v[162:165], v[186:189], v[106:109]
	v_mfma_f32_16x16x32_bf16 v[98:101], v[170:173], v[186:189], v[98:101]
	v_mfma_f32_16x16x32_bf16 v[90:93], v[162:165], v[194:197], v[90:93]
	v_mfma_f32_16x16x32_bf16 v[82:85], v[170:173], v[194:197], v[82:85]
	v_mfma_f32_16x16x32_bf16 v[74:77], v[162:165], v[202:205], v[74:77]
	v_mfma_f32_16x16x32_bf16 v[66:69], v[170:173], v[202:205], v[66:69]
	v_mfma_f32_16x16x32_bf16 v[122:125], v[166:169], v[182:185], v[122:125]
	v_mfma_f32_16x16x32_bf16 v[114:117], v[174:177], v[182:185], v[114:117]
	v_mfma_f32_16x16x32_bf16 v[106:109], v[166:169], v[190:193], v[106:109]
	v_mfma_f32_16x16x32_bf16 v[98:101], v[174:177], v[190:193], v[98:101]
	v_mfma_f32_16x16x32_bf16 v[90:93], v[166:169], v[198:201], v[90:93]
	v_mfma_f32_16x16x32_bf16 v[82:85], v[174:177], v[198:201], v[82:85]
	v_mfma_f32_16x16x32_bf16 v[74:77], v[166:169], v[206:209], v[74:77]
	v_mfma_f32_16x16x32_bf16 v[66:69], v[174:177], v[206:209], v[66:69]
	s_barrier
	s_setprio 0
	s_add_i32 s8, s10, s31
	v_lshl_add_u64 v[210:211], v[210:211], 0, s[82:83]
	s_mov_b32 m0, s8
	ds_read_b128 v[178:181], v153 offset:49152
	ds_read_b128 v[182:185], v153 offset:50176
	ds_read_b128 v[186:189], v153 offset:51200
	ds_read_b128 v[190:193], v153 offset:52224
	ds_read_b128 v[194:197], v153 offset:53248
	ds_read_b128 v[198:201], v153 offset:54272
	ds_read_b128 v[202:205], v153 offset:55296
	ds_read_b128 v[206:209], v153 offset:56320
	global_load_lds_dwordx4 v[210:211], off
	s_add_i32 m0, s8, 0x2000
	s_add_u32 s8, s28, 0x40080
	v_lshl_add_u64 v[210:211], v[212:213], 0, s[82:83]
	s_addc_u32 s9, s29, 0
	s_add_i32 s10, s11, s31
	global_load_lds_dwordx4 v[210:211], off
	v_lshl_add_u64 v[210:211], s[8:9], 0, v[130:131]
	s_mov_b32 m0, s10
	s_nop 0
	global_load_lds_dwordx4 v[210:211], off
	v_lshl_add_u64 v[210:211], s[8:9], 0, v[132:133]
	s_add_i32 m0, s10, 0x2000
	s_nop 0
	global_load_lds_dwordx4 v[210:211], off
	v_lshl_add_u64 v[210:211], v[214:215], 0, s[82:83]
	s_mov_b32 m0, s65
	s_nop 0
	global_load_lds_dwordx4 v[210:211], off
	v_lshl_add_u64 v[210:211], v[216:217], 0, s[82:83]
	s_mov_b32 m0, s66
	s_nop 0
	global_load_lds_dwordx4 v[210:211], off
	s_waitcnt vmcnt(8)
	s_waitcnt lgkmcnt(0)
	s_setprio 1
	s_barrier
	v_mfma_f32_16x16x32_bf16 v[62:65], v[142:145], v[178:181], v[62:65]
	v_mfma_f32_16x16x32_bf16 v[54:57], v[154:157], v[178:181], v[54:57]
	v_mfma_f32_16x16x32_bf16 v[46:49], v[142:145], v[186:189], v[46:49]
	v_mfma_f32_16x16x32_bf16 v[38:41], v[154:157], v[186:189], v[38:41]
	v_mfma_f32_16x16x32_bf16 v[30:33], v[142:145], v[194:197], v[30:33]
	v_mfma_f32_16x16x32_bf16 v[22:25], v[154:157], v[194:197], v[22:25]
	v_mfma_f32_16x16x32_bf16 v[14:17], v[142:145], v[202:205], v[14:17]
	v_mfma_f32_16x16x32_bf16 v[6:9], v[154:157], v[202:205], v[6:9]
	v_mfma_f32_16x16x32_bf16 v[62:65], v[146:149], v[182:185], v[62:65]
	v_mfma_f32_16x16x32_bf16 v[54:57], v[158:161], v[182:185], v[54:57]
	v_mfma_f32_16x16x32_bf16 v[46:49], v[146:149], v[190:193], v[46:49]
	v_mfma_f32_16x16x32_bf16 v[38:41], v[158:161], v[190:193], v[38:41]
	v_mfma_f32_16x16x32_bf16 v[30:33], v[146:149], v[198:201], v[30:33]
	v_mfma_f32_16x16x32_bf16 v[22:25], v[158:161], v[198:201], v[22:25]
	v_mfma_f32_16x16x32_bf16 v[14:17], v[146:149], v[206:209], v[14:17]
	v_mfma_f32_16x16x32_bf16 v[6:9], v[158:161], v[206:209], v[6:9]
	v_mfma_f32_16x16x32_bf16 v[58:61], v[162:165], v[178:181], v[58:61]
	v_mfma_f32_16x16x32_bf16 v[50:53], v[170:173], v[178:181], v[50:53]
	v_mfma_f32_16x16x32_bf16 v[42:45], v[162:165], v[186:189], v[42:45]
	v_mfma_f32_16x16x32_bf16 v[34:37], v[170:173], v[186:189], v[34:37]
	v_mfma_f32_16x16x32_bf16 v[26:29], v[162:165], v[194:197], v[26:29]
	v_mfma_f32_16x16x32_bf16 v[18:21], v[170:173], v[194:197], v[18:21]
	v_mfma_f32_16x16x32_bf16 v[10:13], v[162:165], v[202:205], v[10:13]
	v_mfma_f32_16x16x32_bf16 v[2:5], v[170:173], v[202:205], v[2:5]
	v_mfma_f32_16x16x32_bf16 v[58:61], v[166:169], v[182:185], v[58:61]
	v_mfma_f32_16x16x32_bf16 v[50:53], v[174:177], v[182:185], v[50:53]
	v_mfma_f32_16x16x32_bf16 v[42:45], v[166:169], v[190:193], v[42:45]
	v_mfma_f32_16x16x32_bf16 v[34:37], v[174:177], v[190:193], v[34:37]
	v_mfma_f32_16x16x32_bf16 v[26:29], v[166:169], v[198:201], v[26:29]
	v_mfma_f32_16x16x32_bf16 v[18:21], v[174:177], v[198:201], v[18:21]
	v_mfma_f32_16x16x32_bf16 v[10:13], v[166:169], v[206:209], v[10:13]
	v_mfma_f32_16x16x32_bf16 v[2:5], v[174:177], v[206:209], v[2:5]
	s_barrier
	s_setprio 0
	s_add_i32 s85, s85, 2
	s_add_u32 s58, s58, 0x100
	s_addc_u32 s59, s59, 0
	s_add_u32 s73, s73, 0x100
	s_addc_u32 s84, s84, 0
	s_cmp_gt_u32 s85, 13
	s_cbranch_scc0 .LBB0_50
	s_andn2_b64 vcc, s[48:49], s[42:43]
	s_cbranch_vccz .LBB0_53
	s_barrier
.LBB0_53:
	v_lshl_or_b32 v144, s6, 7, v152
	s_sub_i32 s6, s7, s5
	v_lshl_add_u32 v155, s6, 10, v151
	ds_read2_b32 v[148:149], v155 offset1:16
	v_lshl_add_u32 v154, s7, 8, v1
	v_ashrrev_i32_e32 v145, 31, v144
	v_mov_b64_e32 v[142:143], s[80:81]
	v_mad_i64_i32 v[146:147], s[6:7], v154, s86, v[142:143]
	s_waitcnt lgkmcnt(0)
	v_pk_mul_f32 v[126:127], v[126:127], v[148:149] op_sel_hi:[1,0]
	v_pk_mul_f32 v[122:123], v[122:123], v[148:149] op_sel_hi:[1,0]
	v_pk_mul_f32 v[156:157], v[126:127], s[96:97] op_sel_hi:[1,0]
	v_exp_f32_e32 v156, v156
	v_exp_f32_e32 v157, v157
	v_pk_mul_f32 v[124:125], v[124:125], v[148:149] op_sel_hi:[1,0]
	v_pk_mul_f32 v[118:119], v[118:119], v[148:149] op_sel_hi:[1,0]
	v_pk_add_f32 v[156:157], v[156:157], 1.0 op_sel_hi:[1,0]
	v_rcp_f32_e32 v156, v156
	v_rcp_f32_e32 v157, v157
	v_pk_mul_f32 v[114:115], v[114:115], v[148:149] op_sel_hi:[1,0]
	v_pk_mul_f32 v[116:117], v[116:117], v[148:149] op_sel_hi:[1,0]
	v_lshlrev_b64 v[144:145], 1, v[144:145]
	v_pk_mul_f32 v[126:127], v[126:127], v[156:157]
	v_lshl_add_u64 v[146:147], v[146:147], 0, v[144:145]
	v_pk_mul_f32 v[122:123], v[122:123], v[126:127]
	v_pk_mul_f32 v[126:127], v[128:129], v[148:149] op_sel_hi:[1,0]
	s_mov_b64 s[28:29], -1
	v_pk_mul_f32 v[128:129], v[126:127], s[96:97] op_sel_hi:[1,0]
	v_exp_f32_e32 v128, v128
	v_exp_f32_e32 v129, v129
	s_andn2_b64 vcc, exec, s[42:43]
	v_pk_add_f32 v[128:129], v[128:129], 1.0 op_sel_hi:[1,0]
	v_rcp_f32_e32 v128, v128
	v_rcp_f32_e32 v129, v129
	s_nop 0
	v_pk_mul_f32 v[126:127], v[126:127], v[128:129]
	v_pk_mul_f32 v[124:125], v[124:125], v[126:127]
	v_pk_mul_f32 v[126:127], v[118:119], s[96:97] op_sel_hi:[1,0]
	v_exp_f32_e32 v126, v126
	v_exp_f32_e32 v127, v127
	s_nop 0
	v_pk_add_f32 v[126:127], v[126:127], 1.0 op_sel_hi:[1,0]
	v_rcp_f32_e32 v126, v126
	v_rcp_f32_e32 v127, v127
	s_nop 0
	v_pk_mul_f32 v[118:119], v[118:119], v[126:127]
	v_pk_mul_f32 v[118:119], v[114:115], v[118:119]
	v_pk_mul_f32 v[114:115], v[120:121], v[148:149] op_sel_hi:[1,0]
	v_pk_mul_f32 v[120:121], v[114:115], s[96:97] op_sel_hi:[1,0]
	v_exp_f32_e32 v120, v120
	v_exp_f32_e32 v121, v121
	s_nop 0
	v_pk_add_f32 v[120:121], v[120:121], 1.0 op_sel_hi:[1,0]
	v_rcp_f32_e32 v120, v120
	v_rcp_f32_e32 v121, v121
	s_nop 0
	v_pk_mul_f32 v[114:115], v[114:115], v[120:121]
	v_pk_mul_f32 v[120:121], v[116:117], v[114:115]
	v_cvt_pk_bf16_f32 v114, v122, v123
	v_cvt_pk_bf16_f32 v115, v124, v125
	v_cvt_pk_bf16_f32 v116, v118, v119
	v_cvt_pk_bf16_f32 v117, v120, v121
	global_store_dwordx4 v[146:147], v[114:117], off sc1
	s_nop 1
	v_mov_b32_e32 v116, v149
	v_pk_mul_f32 v[110:111], v[110:111], v[116:117] op_sel_hi:[1,0]
	v_or_b32_e32 v114, 16, v154
	v_mul_f32_e32 v117, 0xbfb8aa3b, v110
	v_exp_f32_e32 v117, v117
	v_mad_i64_i32 v[114:115], s[6:7], v114, s86, v[142:143]
	v_lshl_add_u64 v[114:115], v[114:115], 0, v[144:145]
	v_add_f32_e32 v117, 1.0, v117
	v_rcp_f32_e32 v118, v117
	v_pk_mul_f32 v[106:107], v[106:107], v[116:117] op_sel_hi:[1,0]
	v_mul_f32_e32 v117, 0xbfb8aa3b, v111
	v_exp_f32_e32 v117, v117
	s_nop 0
	v_add_f32_e32 v117, 1.0, v117
	v_rcp_f32_e32 v119, v117
	v_pk_mul_f32 v[108:109], v[108:109], v[116:117] op_sel_hi:[1,0]
	v_pk_mul_f32 v[102:103], v[102:103], v[116:117] op_sel_hi:[1,0]
	v_pk_mul_f32 v[98:99], v[98:99], v[116:117] op_sel_hi:[1,0]
	v_pk_mul_f32 v[110:111], v[110:111], v[118:119]
	v_pk_mul_f32 v[100:101], v[100:101], v[116:117] op_sel_hi:[1,0]
	v_pk_mul_f32 v[106:107], v[106:107], v[110:111]
	v_pk_mul_f32 v[110:111], v[112:113], v[116:117] op_sel_hi:[1,0]
	v_pk_mul_f32 v[112:113], v[110:111], s[96:97] op_sel_hi:[1,0]
	v_exp_f32_e32 v112, v112
	v_exp_f32_e32 v113, v113
	s_nop 0
	v_pk_add_f32 v[112:113], v[112:113], 1.0 op_sel_hi:[1,0]
	v_rcp_f32_e32 v112, v112
	v_rcp_f32_e32 v113, v113
	s_nop 0
	v_pk_mul_f32 v[110:111], v[110:111], v[112:113]
	v_pk_mul_f32 v[108:109], v[108:109], v[110:111]
	v_pk_mul_f32 v[110:111], v[102:103], s[96:97] op_sel_hi:[1,0]
	v_exp_f32_e32 v110, v110
	v_exp_f32_e32 v111, v111
	s_nop 0
	v_pk_add_f32 v[110:111], v[110:111], 1.0 op_sel_hi:[1,0]
	v_rcp_f32_e32 v110, v110
	v_rcp_f32_e32 v111, v111
	s_nop 0
	v_pk_mul_f32 v[102:103], v[102:103], v[110:111]
	v_pk_mul_f32 v[102:103], v[98:99], v[102:103]
	v_pk_mul_f32 v[98:99], v[104:105], v[116:117] op_sel_hi:[1,0]
	v_pk_mul_f32 v[104:105], v[98:99], s[96:97] op_sel_hi:[1,0]
	v_exp_f32_e32 v104, v104
	v_exp_f32_e32 v105, v105
	s_nop 0
	v_pk_add_f32 v[104:105], v[104:105], 1.0 op_sel_hi:[1,0]
	v_rcp_f32_e32 v104, v104
	v_rcp_f32_e32 v105, v105
	s_nop 0
	v_pk_mul_f32 v[98:99], v[98:99], v[104:105]
	v_pk_mul_f32 v[104:105], v[100:101], v[98:99]
	v_cvt_pk_bf16_f32 v98, v106, v107
	v_cvt_pk_bf16_f32 v99, v108, v109
	v_cvt_pk_bf16_f32 v100, v102, v103
	v_cvt_pk_bf16_f32 v101, v104, v105
	global_store_dwordx4 v[114:115], v[98:101], off sc1
	ds_read2_b32 v[100:101], v155 offset0:32 offset1:48
	s_waitcnt lgkmcnt(0)
	v_pk_mul_f32 v[94:95], v[94:95], v[100:101] op_sel_hi:[1,0]
	v_pk_mul_f32 v[102:103], v[94:95], s[96:97] op_sel_hi:[1,0]
	v_exp_f32_e32 v102, v102
	v_exp_f32_e32 v103, v103
	v_pk_mul_f32 v[90:91], v[90:91], v[100:101] op_sel_hi:[1,0]
	v_pk_mul_f32 v[92:93], v[92:93], v[100:101] op_sel_hi:[1,0]
	v_pk_add_f32 v[102:103], v[102:103], 1.0 op_sel_hi:[1,0]
	v_rcp_f32_e32 v102, v102
	v_rcp_f32_e32 v103, v103
	v_pk_mul_f32 v[86:87], v[86:87], v[100:101] op_sel_hi:[1,0]
	v_pk_mul_f32 v[82:83], v[82:83], v[100:101] op_sel_hi:[1,0]
	v_or_b32_e32 v98, 32, v154
	v_pk_mul_f32 v[94:95], v[94:95], v[102:103]
	v_pk_mul_f32 v[84:85], v[84:85], v[100:101] op_sel_hi:[1,0]
	v_pk_mul_f32 v[90:91], v[90:91], v[94:95]
	v_pk_mul_f32 v[94:95], v[96:97], v[100:101] op_sel_hi:[1,0]
	v_mad_i64_i32 v[98:99], s[6:7], v98, s86, v[142:143]
	v_pk_mul_f32 v[96:97], v[94:95], s[96:97] op_sel_hi:[1,0]
	v_exp_f32_e32 v96, v96
	v_exp_f32_e32 v97, v97
	v_lshl_add_u64 v[98:99], v[98:99], 0, v[144:145]
	v_pk_add_f32 v[96:97], v[96:97], 1.0 op_sel_hi:[1,0]
	v_rcp_f32_e32 v96, v96
	v_rcp_f32_e32 v97, v97
	s_nop 0
	v_pk_mul_f32 v[94:95], v[94:95], v[96:97]
	v_pk_mul_f32 v[92:93], v[92:93], v[94:95]
	v_pk_mul_f32 v[94:95], v[86:87], s[96:97] op_sel_hi:[1,0]
	v_exp_f32_e32 v94, v94
	v_exp_f32_e32 v95, v95
	s_nop 0
	v_pk_add_f32 v[94:95], v[94:95], 1.0 op_sel_hi:[1,0]
	v_rcp_f32_e32 v94, v94
	v_rcp_f32_e32 v95, v95
	s_nop 0
	v_pk_mul_f32 v[86:87], v[86:87], v[94:95]
	v_pk_mul_f32 v[86:87], v[82:83], v[86:87]
	v_pk_mul_f32 v[82:83], v[88:89], v[100:101] op_sel_hi:[1,0]
	v_pk_mul_f32 v[88:89], v[82:83], s[96:97] op_sel_hi:[1,0]
	v_exp_f32_e32 v88, v88
	v_exp_f32_e32 v89, v89
	s_nop 0
	v_pk_add_f32 v[88:89], v[88:89], 1.0 op_sel_hi:[1,0]
	v_rcp_f32_e32 v88, v88
	v_rcp_f32_e32 v89, v89
	s_nop 0
	v_pk_mul_f32 v[82:83], v[82:83], v[88:89]
	v_pk_mul_f32 v[88:89], v[84:85], v[82:83]
	v_cvt_pk_bf16_f32 v82, v90, v91
	v_cvt_pk_bf16_f32 v83, v92, v93
	v_cvt_pk_bf16_f32 v84, v86, v87
	v_cvt_pk_bf16_f32 v85, v88, v89
	global_store_dwordx4 v[98:99], v[82:85], off sc1
	s_nop 1
	v_mov_b32_e32 v84, v101
	v_pk_mul_f32 v[78:79], v[78:79], v[84:85] op_sel_hi:[1,0]
	v_or_b32_e32 v82, 48, v154
	v_mul_f32_e32 v85, 0xbfb8aa3b, v78
	v_exp_f32_e32 v85, v85
	v_mad_i64_i32 v[82:83], s[6:7], v82, s86, v[142:143]
	v_lshl_add_u64 v[82:83], v[82:83], 0, v[144:145]
	v_add_f32_e32 v85, 1.0, v85
	v_rcp_f32_e32 v86, v85
	v_pk_mul_f32 v[74:75], v[74:75], v[84:85] op_sel_hi:[1,0]
	v_mul_f32_e32 v85, 0xbfb8aa3b, v79
	v_exp_f32_e32 v85, v85
	s_nop 0
	v_add_f32_e32 v85, 1.0, v85
	v_rcp_f32_e32 v87, v85
	v_pk_mul_f32 v[76:77], v[76:77], v[84:85] op_sel_hi:[1,0]
	v_pk_mul_f32 v[70:71], v[70:71], v[84:85] op_sel_hi:[1,0]
	v_pk_mul_f32 v[66:67], v[66:67], v[84:85] op_sel_hi:[1,0]
	v_pk_mul_f32 v[78:79], v[78:79], v[86:87]
	v_pk_mul_f32 v[68:69], v[68:69], v[84:85] op_sel_hi:[1,0]
	v_pk_mul_f32 v[74:75], v[74:75], v[78:79]
	v_pk_mul_f32 v[78:79], v[80:81], v[84:85] op_sel_hi:[1,0]
	v_pk_mul_f32 v[80:81], v[78:79], s[96:97] op_sel_hi:[1,0]
	v_exp_f32_e32 v80, v80
	v_exp_f32_e32 v81, v81
	s_nop 0
	v_pk_add_f32 v[80:81], v[80:81], 1.0 op_sel_hi:[1,0]
	v_rcp_f32_e32 v80, v80
	v_rcp_f32_e32 v81, v81
	s_nop 0
	v_pk_mul_f32 v[78:79], v[78:79], v[80:81]
	v_pk_mul_f32 v[76:77], v[76:77], v[78:79]
	v_pk_mul_f32 v[78:79], v[70:71], s[96:97] op_sel_hi:[1,0]
	v_exp_f32_e32 v78, v78
	v_exp_f32_e32 v79, v79
	s_nop 0
	v_pk_add_f32 v[78:79], v[78:79], 1.0 op_sel_hi:[1,0]
	v_rcp_f32_e32 v78, v78
	v_rcp_f32_e32 v79, v79
	s_nop 0
	v_pk_mul_f32 v[70:71], v[70:71], v[78:79]
	v_pk_mul_f32 v[70:71], v[66:67], v[70:71]
	v_pk_mul_f32 v[66:67], v[72:73], v[84:85] op_sel_hi:[1,0]
	v_pk_mul_f32 v[72:73], v[66:67], s[96:97] op_sel_hi:[1,0]
	v_exp_f32_e32 v72, v72
	v_exp_f32_e32 v73, v73
	s_nop 0
	v_pk_add_f32 v[72:73], v[72:73], 1.0 op_sel_hi:[1,0]
	v_rcp_f32_e32 v72, v72
	v_rcp_f32_e32 v73, v73
	s_nop 0
	v_pk_mul_f32 v[66:67], v[66:67], v[72:73]
	v_pk_mul_f32 v[72:73], v[68:69], v[66:67]
	v_cvt_pk_bf16_f32 v66, v74, v75
	v_cvt_pk_bf16_f32 v67, v76, v77
	v_cvt_pk_bf16_f32 v68, v70, v71
	v_cvt_pk_bf16_f32 v69, v72, v73
	global_store_dwordx4 v[82:83], v[66:69], off sc1
	ds_read2_b32 v[68:69], v155 offset0:128 offset1:144
	s_waitcnt lgkmcnt(0)
	v_pk_mul_f32 v[62:63], v[62:63], v[68:69] op_sel_hi:[1,0]
	v_pk_mul_f32 v[70:71], v[62:63], s[96:97] op_sel_hi:[1,0]
	v_exp_f32_e32 v70, v70
	v_exp_f32_e32 v71, v71
	v_pk_mul_f32 v[58:59], v[58:59], v[68:69] op_sel_hi:[1,0]
	v_pk_mul_f32 v[60:61], v[60:61], v[68:69] op_sel_hi:[1,0]
	v_pk_add_f32 v[70:71], v[70:71], 1.0 op_sel_hi:[1,0]
	v_rcp_f32_e32 v70, v70
	v_rcp_f32_e32 v71, v71
	v_pk_mul_f32 v[54:55], v[54:55], v[68:69] op_sel_hi:[1,0]
	v_pk_mul_f32 v[50:51], v[50:51], v[68:69] op_sel_hi:[1,0]
	v_add_u32_e32 v66, 0x80, v154
	v_pk_mul_f32 v[62:63], v[62:63], v[70:71]
	v_pk_mul_f32 v[52:53], v[52:53], v[68:69] op_sel_hi:[1,0]
	v_pk_mul_f32 v[58:59], v[58:59], v[62:63]
	v_pk_mul_f32 v[62:63], v[64:65], v[68:69] op_sel_hi:[1,0]
	v_mad_i64_i32 v[66:67], s[6:7], v66, s86, v[142:143]
	v_pk_mul_f32 v[64:65], v[62:63], s[96:97] op_sel_hi:[1,0]
	v_exp_f32_e32 v64, v64
	v_exp_f32_e32 v65, v65
	v_lshl_add_u64 v[66:67], v[66:67], 0, v[144:145]
	v_pk_add_f32 v[64:65], v[64:65], 1.0 op_sel_hi:[1,0]
	v_rcp_f32_e32 v64, v64
	v_rcp_f32_e32 v65, v65
	s_nop 0
	v_pk_mul_f32 v[62:63], v[62:63], v[64:65]
	v_pk_mul_f32 v[60:61], v[60:61], v[62:63]
	v_pk_mul_f32 v[62:63], v[54:55], s[96:97] op_sel_hi:[1,0]
	v_exp_f32_e32 v62, v62
	v_exp_f32_e32 v63, v63
	s_nop 0
	v_pk_add_f32 v[62:63], v[62:63], 1.0 op_sel_hi:[1,0]
	v_rcp_f32_e32 v62, v62
	v_rcp_f32_e32 v63, v63
	s_nop 0
	v_pk_mul_f32 v[54:55], v[54:55], v[62:63]
	v_pk_mul_f32 v[54:55], v[50:51], v[54:55]
	v_pk_mul_f32 v[50:51], v[56:57], v[68:69] op_sel_hi:[1,0]
	v_pk_mul_f32 v[56:57], v[50:51], s[96:97] op_sel_hi:[1,0]
	v_exp_f32_e32 v56, v56
	v_exp_f32_e32 v57, v57
	s_nop 0
	v_pk_add_f32 v[56:57], v[56:57], 1.0 op_sel_hi:[1,0]
	v_rcp_f32_e32 v56, v56
	v_rcp_f32_e32 v57, v57
	s_nop 0
	v_pk_mul_f32 v[50:51], v[50:51], v[56:57]
	v_pk_mul_f32 v[56:57], v[52:53], v[50:51]
	v_cvt_pk_bf16_f32 v50, v58, v59
	v_cvt_pk_bf16_f32 v51, v60, v61
	v_cvt_pk_bf16_f32 v52, v54, v55
	v_cvt_pk_bf16_f32 v53, v56, v57
	global_store_dwordx4 v[66:67], v[50:53], off sc1
	s_nop 1
	v_mov_b32_e32 v52, v69
	v_pk_mul_f32 v[46:47], v[46:47], v[52:53] op_sel_hi:[1,0]
	v_add_u32_e32 v50, 0x90, v154
	v_mul_f32_e32 v53, 0xbfb8aa3b, v46
	v_exp_f32_e32 v53, v53
	v_mad_i64_i32 v[50:51], s[6:7], v50, s86, v[142:143]
	v_lshl_add_u64 v[50:51], v[50:51], 0, v[144:145]
	v_add_f32_e32 v53, 1.0, v53
	v_rcp_f32_e32 v54, v53
	v_pk_mul_f32 v[42:43], v[42:43], v[52:53] op_sel_hi:[1,0]
	v_mul_f32_e32 v53, 0xbfb8aa3b, v47
	v_exp_f32_e32 v53, v53
	s_nop 0
	v_add_f32_e32 v53, 1.0, v53
	v_rcp_f32_e32 v55, v53
	v_pk_mul_f32 v[44:45], v[44:45], v[52:53] op_sel_hi:[1,0]
	v_pk_mul_f32 v[38:39], v[38:39], v[52:53] op_sel_hi:[1,0]
	v_pk_mul_f32 v[34:35], v[34:35], v[52:53] op_sel_hi:[1,0]
	v_pk_mul_f32 v[46:47], v[46:47], v[54:55]
	v_pk_mul_f32 v[36:37], v[36:37], v[52:53] op_sel_hi:[1,0]
	v_pk_mul_f32 v[42:43], v[42:43], v[46:47]
	v_pk_mul_f32 v[46:47], v[48:49], v[52:53] op_sel_hi:[1,0]
	v_pk_mul_f32 v[48:49], v[46:47], s[96:97] op_sel_hi:[1,0]
	v_exp_f32_e32 v48, v48
	v_exp_f32_e32 v49, v49
	s_nop 0
	v_pk_add_f32 v[48:49], v[48:49], 1.0 op_sel_hi:[1,0]
	v_rcp_f32_e32 v48, v48
	v_rcp_f32_e32 v49, v49
	s_nop 0
	v_pk_mul_f32 v[46:47], v[46:47], v[48:49]
	v_pk_mul_f32 v[44:45], v[44:45], v[46:47]
	v_pk_mul_f32 v[46:47], v[38:39], s[96:97] op_sel_hi:[1,0]
	v_exp_f32_e32 v46, v46
	v_exp_f32_e32 v47, v47
	s_nop 0
	v_pk_add_f32 v[46:47], v[46:47], 1.0 op_sel_hi:[1,0]
	v_rcp_f32_e32 v46, v46
	v_rcp_f32_e32 v47, v47
	s_nop 0
	v_pk_mul_f32 v[38:39], v[38:39], v[46:47]
	v_pk_mul_f32 v[38:39], v[34:35], v[38:39]
	v_pk_mul_f32 v[34:35], v[40:41], v[52:53] op_sel_hi:[1,0]
	v_pk_mul_f32 v[40:41], v[34:35], s[96:97] op_sel_hi:[1,0]
	v_exp_f32_e32 v40, v40
	v_exp_f32_e32 v41, v41
	s_nop 0
	v_pk_add_f32 v[40:41], v[40:41], 1.0 op_sel_hi:[1,0]
	v_rcp_f32_e32 v40, v40
	v_rcp_f32_e32 v41, v41
	s_nop 0
	v_pk_mul_f32 v[34:35], v[34:35], v[40:41]
	v_pk_mul_f32 v[40:41], v[36:37], v[34:35]
	v_cvt_pk_bf16_f32 v34, v42, v43
	v_cvt_pk_bf16_f32 v35, v44, v45
	v_cvt_pk_bf16_f32 v36, v38, v39
	v_cvt_pk_bf16_f32 v37, v40, v41
	global_store_dwordx4 v[50:51], v[34:37], off sc1
	ds_read2_b32 v[36:37], v155 offset0:160 offset1:176
	s_waitcnt lgkmcnt(0)
	v_pk_mul_f32 v[30:31], v[30:31], v[36:37] op_sel_hi:[1,0]
	v_pk_mul_f32 v[38:39], v[30:31], s[96:97] op_sel_hi:[1,0]
	v_exp_f32_e32 v38, v38
	v_exp_f32_e32 v39, v39
	v_pk_mul_f32 v[26:27], v[26:27], v[36:37] op_sel_hi:[1,0]
	v_pk_mul_f32 v[28:29], v[28:29], v[36:37] op_sel_hi:[1,0]
	v_pk_add_f32 v[38:39], v[38:39], 1.0 op_sel_hi:[1,0]
	v_rcp_f32_e32 v38, v38
	v_rcp_f32_e32 v39, v39
	v_pk_mul_f32 v[22:23], v[22:23], v[36:37] op_sel_hi:[1,0]
	v_pk_mul_f32 v[18:19], v[18:19], v[36:37] op_sel_hi:[1,0]
	v_add_u32_e32 v34, 0xa0, v154
	v_pk_mul_f32 v[30:31], v[30:31], v[38:39]
	v_pk_mul_f32 v[20:21], v[20:21], v[36:37] op_sel_hi:[1,0]
	v_pk_mul_f32 v[26:27], v[26:27], v[30:31]
	v_pk_mul_f32 v[30:31], v[32:33], v[36:37] op_sel_hi:[1,0]
	v_mad_i64_i32 v[34:35], s[6:7], v34, s86, v[142:143]
	v_pk_mul_f32 v[32:33], v[30:31], s[96:97] op_sel_hi:[1,0]
	v_exp_f32_e32 v32, v32
	v_exp_f32_e32 v33, v33
	v_lshl_add_u64 v[34:35], v[34:35], 0, v[144:145]
	v_pk_add_f32 v[32:33], v[32:33], 1.0 op_sel_hi:[1,0]
	v_rcp_f32_e32 v32, v32
	v_rcp_f32_e32 v33, v33
	s_nop 0
	v_pk_mul_f32 v[30:31], v[30:31], v[32:33]
	v_pk_mul_f32 v[28:29], v[28:29], v[30:31]
	v_pk_mul_f32 v[30:31], v[22:23], s[96:97] op_sel_hi:[1,0]
	v_exp_f32_e32 v30, v30
	v_exp_f32_e32 v31, v31
	s_nop 0
	v_pk_add_f32 v[30:31], v[30:31], 1.0 op_sel_hi:[1,0]
	v_rcp_f32_e32 v30, v30
	v_rcp_f32_e32 v31, v31
	s_nop 0
	v_pk_mul_f32 v[22:23], v[22:23], v[30:31]
	v_pk_mul_f32 v[22:23], v[18:19], v[22:23]
	v_pk_mul_f32 v[18:19], v[24:25], v[36:37] op_sel_hi:[1,0]
	v_pk_mul_f32 v[24:25], v[18:19], s[96:97] op_sel_hi:[1,0]
	v_exp_f32_e32 v24, v24
	v_exp_f32_e32 v25, v25
	s_nop 0
	v_pk_add_f32 v[24:25], v[24:25], 1.0 op_sel_hi:[1,0]
	v_rcp_f32_e32 v24, v24
	v_rcp_f32_e32 v25, v25
	s_nop 0
	v_pk_mul_f32 v[18:19], v[18:19], v[24:25]
	v_pk_mul_f32 v[24:25], v[20:21], v[18:19]
	v_cvt_pk_bf16_f32 v18, v26, v27
	v_cvt_pk_bf16_f32 v19, v28, v29
	v_cvt_pk_bf16_f32 v20, v22, v23
	v_cvt_pk_bf16_f32 v21, v24, v25
	global_store_dwordx4 v[34:35], v[18:21], off sc1
	s_nop 1
	v_mov_b32_e32 v20, v37
	v_pk_mul_f32 v[14:15], v[14:15], v[20:21] op_sel_hi:[1,0]
	v_add_u32_e32 v18, 0xb0, v154
	v_mul_f32_e32 v21, 0xbfb8aa3b, v14
	v_exp_f32_e32 v21, v21
	v_mad_i64_i32 v[18:19], s[6:7], v18, s86, v[142:143]
	v_lshl_add_u64 v[18:19], v[18:19], 0, v[144:145]
	v_add_f32_e32 v21, 1.0, v21
	v_rcp_f32_e32 v22, v21
	v_pk_mul_f32 v[10:11], v[10:11], v[20:21] op_sel_hi:[1,0]
	v_mul_f32_e32 v21, 0xbfb8aa3b, v15
	v_exp_f32_e32 v21, v21
	s_nop 0
	v_add_f32_e32 v21, 1.0, v21
	v_rcp_f32_e32 v23, v21
	v_pk_mul_f32 v[12:13], v[12:13], v[20:21] op_sel_hi:[1,0]
	v_pk_mul_f32 v[6:7], v[6:7], v[20:21] op_sel_hi:[1,0]
	v_pk_mul_f32 v[2:3], v[2:3], v[20:21] op_sel_hi:[1,0]
	v_pk_mul_f32 v[14:15], v[14:15], v[22:23]
	v_pk_mul_f32 v[4:5], v[4:5], v[20:21] op_sel_hi:[1,0]
	v_pk_mul_f32 v[10:11], v[10:11], v[14:15]
	v_pk_mul_f32 v[14:15], v[16:17], v[20:21] op_sel_hi:[1,0]
	v_pk_mul_f32 v[16:17], v[14:15], s[96:97] op_sel_hi:[1,0]
	v_exp_f32_e32 v16, v16
	v_exp_f32_e32 v17, v17
	s_nop 0
	v_pk_add_f32 v[16:17], v[16:17], 1.0 op_sel_hi:[1,0]
	v_rcp_f32_e32 v16, v16
	v_rcp_f32_e32 v17, v17
	s_nop 0
	v_pk_mul_f32 v[14:15], v[14:15], v[16:17]
	v_pk_mul_f32 v[12:13], v[12:13], v[14:15]
	v_pk_mul_f32 v[14:15], v[6:7], s[96:97] op_sel_hi:[1,0]
	v_exp_f32_e32 v14, v14
	v_exp_f32_e32 v15, v15
	s_nop 0
	v_pk_add_f32 v[14:15], v[14:15], 1.0 op_sel_hi:[1,0]
	v_rcp_f32_e32 v14, v14
	v_rcp_f32_e32 v15, v15
	s_nop 0
	v_pk_mul_f32 v[6:7], v[6:7], v[14:15]
	v_pk_mul_f32 v[6:7], v[2:3], v[6:7]
	v_pk_mul_f32 v[2:3], v[8:9], v[20:21] op_sel_hi:[1,0]
	v_pk_mul_f32 v[8:9], v[2:3], s[96:97] op_sel_hi:[1,0]
	v_exp_f32_e32 v8, v8
	v_exp_f32_e32 v9, v9
	s_nop 0
	v_pk_add_f32 v[8:9], v[8:9], 1.0 op_sel_hi:[1,0]
	v_rcp_f32_e32 v8, v8
	v_rcp_f32_e32 v9, v9
	s_nop 0
	v_pk_mul_f32 v[2:3], v[2:3], v[8:9]
	v_pk_mul_f32 v[8:9], v[4:5], v[2:3]
	v_cvt_pk_bf16_f32 v2, v10, v11
	v_cvt_pk_bf16_f32 v3, v12, v13
	v_cvt_pk_bf16_f32 v4, v6, v7
	v_cvt_pk_bf16_f32 v5, v8, v9
	global_store_dwordx4 v[18:19], v[2:5], off sc1
	s_cbranch_vccnz .LBB0_46
	s_andn2_b64 vcc, exec, s[44:45]
	s_cbranch_vccnz .LBB0_45
	s_branch .LBB0_45
